# two grid barriers per layer (after out-proj+LN0, after xq+xa) replaced by 4-workgroup row-panel barriers; other 10 sites keep the 3-hop sharded grid barrier
# speedup vs baseline: 1.0062x; 1.0011x over previous
_Z6mk_fwd4Args:
	s_mov_b32 s100, 0
	s_mov_b32 s101, 0
	s_add_u32 s4, s0, 0xa0
	s_load_dword s3, s[0:1], 0xa0
	s_addc_u32 s5, s1, 0
	v_mov_b32_e32 v2, v0
	v_writelane_b32 v253, s4, 0
	s_nop 1
	v_writelane_b32 v253, s5, 1
	s_movk_i32 s4, 0x400
	v_cmp_gt_i32_e32 vcc, s4, v2
	s_and_saveexec_b64 s[4:5], vcc
	s_cbranch_execz .LBB0_3
	v_add_u32_e32 v1, 0xfffffe00, v2
	v_lshl_add_u32 v2, v2, 2, 0
	v_add_u32_e32 v2, 0x23000, v2
	s_mov_b64 s[6:7], 0
	v_mov_b32_e32 v3, 0
	s_movk_i32 s8, 0x1ff

.LBB0_130:
	s_or_b64 exec, exec, s[0:1]
	s_getreg_b32 s0, hwreg(HW_REG_XCC_ID, 0, 4)
	s_and_b32 s48, s0, 15
	s_waitcnt vmcnt(0)
	s_barrier
	s_and_saveexec_b64 s[0:1], s[52:53]
	s_add_i32 s100, s100, 1
	s_cbranch_execz .LBB0_182
	v_readlane_b32 s98, v253, 2
	v_readlane_b32 s99, v253, 3
	s_nop 0
	s_add_u32 s98, s98, 0x7c000
	s_addc_u32 s99, s99, 0
	s_and_b32 vcc_hi, s2, 7
	s_sub_u32 vcc_lo, 7, vcc_hi
	s_add_u32 vcc_lo, vcc_lo, s3
	s_lshr_b32 vcc_lo, vcc_lo, 3
	s_mul_i32 vcc_lo, vcc_lo, s100
	s_lshl_b32 vcc_hi, vcc_hi, 8
	v_mov_b32_e32 v2, vcc_hi
	v_mov_b32_e32 v4, 1
	s_waitcnt vmcnt(0) lgkmcnt(0)
	global_atomic_add v5, v2, v4, s[98:99] sc0
	v_add_u32_e32 v3, 0x900, v2
	s_waitcnt vmcnt(0)
	v_readfirstlane_b32 vcc_hi, v5
	s_add_i32 vcc_hi, vcc_hi, 1
	s_cmp_eq_u32 vcc_hi, vcc_lo
	s_cbranch_scc0 .Lb3_poll_0
	v_mov_b32_e32 v6, 0x800
	global_atomic_add v5, v6, v4, s[98:99] sc0
	s_min_u32 vcc_lo, s3, 8
	s_mul_i32 vcc_lo, vcc_lo, s100
	s_waitcnt vmcnt(0)
	v_readfirstlane_b32 vcc_hi, v5
	s_add_i32 vcc_hi, vcc_hi, 1
	s_cmp_eq_u32 vcc_hi, vcc_lo
	s_cbranch_scc0 .Lb3_poll_0
	v_mov_b32_e32 v6, 0x900
	global_atomic_add v6, v4, s[98:99]
	global_atomic_add v6, v4, s[98:99] offset:256
	global_atomic_add v6, v4, s[98:99] offset:512
	global_atomic_add v6, v4, s[98:99] offset:768
	global_atomic_add v6, v4, s[98:99] offset:1024
	global_atomic_add v6, v4, s[98:99] offset:1280
	global_atomic_add v6, v4, s[98:99] offset:1536
	global_atomic_add v6, v4, s[98:99] offset:1792

.Lb3_p_0:
	global_load_dword v5, v3, s[98:99] sc1
	s_waitcnt vmcnt(0)
	v_readfirstlane_b32 vcc_lo, v5
	s_cmp_ge_u32 vcc_lo, s100
	s_cbranch_scc1 .Lb3_ok_0
	s_sleep 1
	s_sub_u32 m0, m0, 1
	s_cmp_eq_u32 m0, 0
	s_cbranch_scc0 .Lb3_p_0

.LBB0_226:
	s_getreg_b32 s0, hwreg(HW_REG_XCC_ID, 0, 4)
	s_and_b32 s9, s0, 15
	s_waitcnt vmcnt(0)
	s_waitcnt vmcnt(0)
	s_barrier
	s_and_saveexec_b64 s[0:1], s[52:53]
	v_readlane_b32 s24, v255, 22
	s_add_i32 s100, s100, 1
	s_cbranch_execz .LBB0_278
	v_readlane_b32 s98, v253, 2
	v_readlane_b32 s99, v253, 3
	s_nop 0
	s_add_u32 s98, s98, 0x7c000
	s_addc_u32 s99, s99, 0
	s_and_b32 vcc_hi, s2, 7
	s_sub_u32 vcc_lo, 7, vcc_hi
	s_add_u32 vcc_lo, vcc_lo, s3
	s_lshr_b32 vcc_lo, vcc_lo, 3
	s_mul_i32 vcc_lo, vcc_lo, s100
	s_lshl_b32 vcc_hi, vcc_hi, 8
	v_mov_b32_e32 v2, vcc_hi
	v_mov_b32_e32 v4, 1
	s_waitcnt vmcnt(0) lgkmcnt(0)
	global_atomic_add v5, v2, v4, s[98:99] sc0
	v_add_u32_e32 v3, 0x900, v2
	s_waitcnt vmcnt(0)
	v_readfirstlane_b32 vcc_hi, v5
	s_add_i32 vcc_hi, vcc_hi, 1
	s_cmp_eq_u32 vcc_hi, vcc_lo
	s_cbranch_scc0 .Lb3_poll_1
	v_mov_b32_e32 v6, 0x800
	global_atomic_add v5, v6, v4, s[98:99] sc0
	s_min_u32 vcc_lo, s3, 8
	s_mul_i32 vcc_lo, vcc_lo, s100
	s_waitcnt vmcnt(0)
	v_readfirstlane_b32 vcc_hi, v5
	s_add_i32 vcc_hi, vcc_hi, 1
	s_cmp_eq_u32 vcc_hi, vcc_lo
	s_cbranch_scc0 .Lb3_poll_1
	v_mov_b32_e32 v6, 0x900
	global_atomic_add v6, v4, s[98:99]
	global_atomic_add v6, v4, s[98:99] offset:256
	global_atomic_add v6, v4, s[98:99] offset:512
	global_atomic_add v6, v4, s[98:99] offset:768
	global_atomic_add v6, v4, s[98:99] offset:1024
	global_atomic_add v6, v4, s[98:99] offset:1280
	global_atomic_add v6, v4, s[98:99] offset:1536
	global_atomic_add v6, v4, s[98:99] offset:1792

.LBB0_292:
	s_getreg_b32 s0, hwreg(HW_REG_XCC_ID, 0, 4)
	s_and_b32 s9, s0, 15
	s_waitcnt vmcnt(0)
	v_readlane_b32 s52, v253, 4
	v_readlane_b32 s53, v253, 5
	s_barrier
	s_and_saveexec_b64 s[0:1], s[52:53]
	v_readlane_b32 s54, v255, 8
	v_readlane_b32 s55, v255, 9
	s_add_i32 s100, s100, 1
	s_cbranch_execz .LBB0_344
	v_readlane_b32 s98, v253, 2
	v_readlane_b32 s99, v253, 3
	s_nop 0
	s_add_u32 s98, s98, 0x7c000
	s_addc_u32 s99, s99, 0
	s_and_b32 vcc_hi, s2, 7
	s_sub_u32 vcc_lo, 7, vcc_hi
	s_add_u32 vcc_lo, vcc_lo, s3
	s_lshr_b32 vcc_lo, vcc_lo, 3
	s_mul_i32 vcc_lo, vcc_lo, s100
	s_lshl_b32 vcc_hi, vcc_hi, 8
	v_mov_b32_e32 v2, vcc_hi
	v_mov_b32_e32 v4, 1
	s_waitcnt vmcnt(0) lgkmcnt(0)
	global_atomic_add v5, v2, v4, s[98:99] sc0
	v_add_u32_e32 v3, 0x900, v2
	s_waitcnt vmcnt(0)
	v_readfirstlane_b32 vcc_hi, v5
	s_add_i32 vcc_hi, vcc_hi, 1
	s_cmp_eq_u32 vcc_hi, vcc_lo
	s_cbranch_scc0 .Lb3_poll_2
	v_mov_b32_e32 v6, 0x800
	global_atomic_add v5, v6, v4, s[98:99] sc0
	s_min_u32 vcc_lo, s3, 8
	s_mul_i32 vcc_lo, vcc_lo, s100
	s_waitcnt vmcnt(0)
	v_readfirstlane_b32 vcc_hi, v5
	s_add_i32 vcc_hi, vcc_hi, 1
	s_cmp_eq_u32 vcc_hi, vcc_lo
	s_cbranch_scc0 .Lb3_poll_2
	v_mov_b32_e32 v6, 0x900
	global_atomic_add v6, v4, s[98:99]
	global_atomic_add v6, v4, s[98:99] offset:256
	global_atomic_add v6, v4, s[98:99] offset:512
	global_atomic_add v6, v4, s[98:99] offset:768
	global_atomic_add v6, v4, s[98:99] offset:1024
	global_atomic_add v6, v4, s[98:99] offset:1280
	global_atomic_add v6, v4, s[98:99] offset:1536
	global_atomic_add v6, v4, s[98:99] offset:1792

.LBB0_369:
	s_getreg_b32 s0, hwreg(HW_REG_XCC_ID, 0, 4)
	s_and_b32 s9, s0, 15
	s_waitcnt vmcnt(0)
	s_waitcnt vmcnt(0)
	s_barrier
	s_and_saveexec_b64 s[0:1], s[52:53]
	s_add_i32 s100, s100, 1
	s_cbranch_execz .LBB0_421
	v_readlane_b32 s98, v253, 2
	v_readlane_b32 s99, v253, 3
	s_nop 0
	s_add_u32 s98, s98, 0x7c000
	s_addc_u32 s99, s99, 0
	s_and_b32 vcc_hi, s2, 7
	s_sub_u32 vcc_lo, 7, vcc_hi
	s_add_u32 vcc_lo, vcc_lo, s3
	s_lshr_b32 vcc_lo, vcc_lo, 3
	s_mul_i32 vcc_lo, vcc_lo, s100
	s_lshl_b32 vcc_hi, vcc_hi, 8
	v_mov_b32_e32 v2, vcc_hi
	v_mov_b32_e32 v4, 1
	s_waitcnt vmcnt(0) lgkmcnt(0)
	global_atomic_add v5, v2, v4, s[98:99] sc0
	v_add_u32_e32 v3, 0x900, v2
	s_waitcnt vmcnt(0)
	v_readfirstlane_b32 vcc_hi, v5
	s_add_i32 vcc_hi, vcc_hi, 1
	s_cmp_eq_u32 vcc_hi, vcc_lo
	s_cbranch_scc0 .Lb3_poll_3
	v_mov_b32_e32 v6, 0x800
	global_atomic_add v5, v6, v4, s[98:99] sc0
	s_min_u32 vcc_lo, s3, 8
	s_mul_i32 vcc_lo, vcc_lo, s100
	s_waitcnt vmcnt(0)
	v_readfirstlane_b32 vcc_hi, v5
	s_add_i32 vcc_hi, vcc_hi, 1
	s_cmp_eq_u32 vcc_hi, vcc_lo
	s_cbranch_scc0 .Lb3_poll_3
	v_mov_b32_e32 v6, 0x900
	global_atomic_add v6, v4, s[98:99]
	global_atomic_add v6, v4, s[98:99] offset:256
	global_atomic_add v6, v4, s[98:99] offset:512
	global_atomic_add v6, v4, s[98:99] offset:768
	global_atomic_add v6, v4, s[98:99] offset:1024
	global_atomic_add v6, v4, s[98:99] offset:1280
	global_atomic_add v6, v4, s[98:99] offset:1536
	global_atomic_add v6, v4, s[98:99] offset:1792

.LBB0_480:
	s_getreg_b32 s0, hwreg(HW_REG_XCC_ID, 0, 4)
	s_and_b32 s12, s0, 15
	s_waitcnt vmcnt(0)
	s_barrier
	s_and_saveexec_b64 s[0:1], s[52:53]
	s_add_i32 s100, s100, 1
	s_cbranch_execz .LBB0_532
	v_readlane_b32 s98, v253, 2
	v_readlane_b32 s99, v253, 3
	s_nop 0
	s_add_u32 s98, s98, 0x7c000
	s_addc_u32 s99, s99, 0
	s_and_b32 vcc_hi, s2, 7
	s_sub_u32 vcc_lo, 7, vcc_hi
	s_add_u32 vcc_lo, vcc_lo, s3
	s_lshr_b32 vcc_lo, vcc_lo, 3
	s_mul_i32 vcc_lo, vcc_lo, s100
	s_lshl_b32 vcc_hi, vcc_hi, 8
	v_mov_b32_e32 v2, vcc_hi
	v_mov_b32_e32 v4, 1
	s_waitcnt vmcnt(0) lgkmcnt(0)
	global_atomic_add v5, v2, v4, s[98:99] sc0
	v_add_u32_e32 v3, 0x900, v2
	s_waitcnt vmcnt(0)
	v_readfirstlane_b32 vcc_hi, v5
	s_add_i32 vcc_hi, vcc_hi, 1
	s_cmp_eq_u32 vcc_hi, vcc_lo
	s_cbranch_scc0 .Lb3_poll_4
	v_mov_b32_e32 v6, 0x800
	global_atomic_add v5, v6, v4, s[98:99] sc0
	s_min_u32 vcc_lo, s3, 8
	s_mul_i32 vcc_lo, vcc_lo, s100
	s_waitcnt vmcnt(0)
	v_readfirstlane_b32 vcc_hi, v5
	s_add_i32 vcc_hi, vcc_hi, 1
	s_cmp_eq_u32 vcc_hi, vcc_lo
	s_cbranch_scc0 .Lb3_poll_4
	v_mov_b32_e32 v6, 0x900
	global_atomic_add v6, v4, s[98:99]
	global_atomic_add v6, v4, s[98:99] offset:256
	global_atomic_add v6, v4, s[98:99] offset:512
	global_atomic_add v6, v4, s[98:99] offset:768
	global_atomic_add v6, v4, s[98:99] offset:1024
	global_atomic_add v6, v4, s[98:99] offset:1280
	global_atomic_add v6, v4, s[98:99] offset:1536
	global_atomic_add v6, v4, s[98:99] offset:1792

.LBB0_569:
	s_or_b64 exec, exec, s[0:1]
	s_getreg_b32 s0, hwreg(HW_REG_XCC_ID, 0, 4)
	s_and_b32 s12, s0, 15
	s_waitcnt vmcnt(0)
	s_barrier
	s_and_saveexec_b64 s[0:1], s[52:53]
	s_add_i32 s100, s100, 1
	s_cbranch_execz .LBB0_621
	v_readlane_b32 s98, v253, 2
	v_readlane_b32 s99, v253, 3
	s_nop 0
	s_add_u32 s98, s98, 0x7c000
	s_addc_u32 s99, s99, 0
	s_and_b32 vcc_hi, s2, 7
	s_sub_u32 vcc_lo, 7, vcc_hi
	s_add_u32 vcc_lo, vcc_lo, s3
	s_lshr_b32 vcc_lo, vcc_lo, 3
	s_mul_i32 vcc_lo, vcc_lo, s100
	s_lshl_b32 vcc_hi, vcc_hi, 8
	v_mov_b32_e32 v2, vcc_hi
	v_mov_b32_e32 v4, 1
	s_waitcnt vmcnt(0) lgkmcnt(0)
	global_atomic_add v5, v2, v4, s[98:99] sc0
	v_add_u32_e32 v3, 0x900, v2
	s_waitcnt vmcnt(0)
	v_readfirstlane_b32 vcc_hi, v5
	s_add_i32 vcc_hi, vcc_hi, 1
	s_cmp_eq_u32 vcc_hi, vcc_lo
	s_cbranch_scc0 .Lb3_poll_5
	v_mov_b32_e32 v6, 0x800
	global_atomic_add v5, v6, v4, s[98:99] sc0
	s_min_u32 vcc_lo, s3, 8
	s_mul_i32 vcc_lo, vcc_lo, s100
	s_waitcnt vmcnt(0)
	v_readfirstlane_b32 vcc_hi, v5
	s_add_i32 vcc_hi, vcc_hi, 1
	s_cmp_eq_u32 vcc_hi, vcc_lo
	s_cbranch_scc0 .Lb3_poll_5
	v_mov_b32_e32 v6, 0x900
	global_atomic_add v6, v4, s[98:99]
	global_atomic_add v6, v4, s[98:99] offset:256
	global_atomic_add v6, v4, s[98:99] offset:512
	global_atomic_add v6, v4, s[98:99] offset:768
	global_atomic_add v6, v4, s[98:99] offset:1024
	global_atomic_add v6, v4, s[98:99] offset:1280
	global_atomic_add v6, v4, s[98:99] offset:1536
	global_atomic_add v6, v4, s[98:99] offset:1792

.LBB0_691:
	s_getreg_b32 s0, hwreg(HW_REG_XCC_ID, 0, 4)
	s_and_b32 s10, s0, 15
	s_waitcnt vmcnt(0)
	s_barrier
	s_and_saveexec_b64 s[0:1], s[52:53]
	v_readlane_b32 s14, v255, 16
	v_readlane_b32 s15, v255, 17
	s_add_i32 s100, s100, 1
	s_cbranch_execz .LBB0_743
	v_readlane_b32 s98, v253, 2
	v_readlane_b32 s99, v253, 3
	s_nop 0
	s_add_u32 s98, s98, 0x7c000
	s_addc_u32 s99, s99, 0
	s_and_b32 vcc_hi, s2, 7
	s_sub_u32 vcc_lo, 7, vcc_hi
	s_add_u32 vcc_lo, vcc_lo, s3
	s_lshr_b32 vcc_lo, vcc_lo, 3
	s_mul_i32 vcc_lo, vcc_lo, s100
	s_lshl_b32 vcc_hi, vcc_hi, 8
	v_mov_b32_e32 v2, vcc_hi
	v_mov_b32_e32 v4, 1
	s_waitcnt vmcnt(0) lgkmcnt(0)
	global_atomic_add v5, v2, v4, s[98:99] sc0
	v_add_u32_e32 v3, 0x900, v2
	s_waitcnt vmcnt(0)
	v_readfirstlane_b32 vcc_hi, v5
	s_add_i32 vcc_hi, vcc_hi, 1
	s_cmp_eq_u32 vcc_hi, vcc_lo
	s_cbranch_scc0 .Lb3_poll_6
	v_mov_b32_e32 v6, 0x800
	global_atomic_add v5, v6, v4, s[98:99] sc0
	s_min_u32 vcc_lo, s3, 8
	s_mul_i32 vcc_lo, vcc_lo, s100
	s_waitcnt vmcnt(0)
	v_readfirstlane_b32 vcc_hi, v5
	s_add_i32 vcc_hi, vcc_hi, 1
	s_cmp_eq_u32 vcc_hi, vcc_lo
	s_cbranch_scc0 .Lb3_poll_6
	v_mov_b32_e32 v6, 0x900
	global_atomic_add v6, v4, s[98:99]
	global_atomic_add v6, v4, s[98:99] offset:256
	global_atomic_add v6, v4, s[98:99] offset:512
	global_atomic_add v6, v4, s[98:99] offset:768
	global_atomic_add v6, v4, s[98:99] offset:1024
	global_atomic_add v6, v4, s[98:99] offset:1280
	global_atomic_add v6, v4, s[98:99] offset:1536
	global_atomic_add v6, v4, s[98:99] offset:1792

.LBB0_866:
	s_getreg_b32 s0, hwreg(HW_REG_XCC_ID, 0, 4)
	s_and_b32 s10, s0, 15
	s_waitcnt vmcnt(0)
	s_waitcnt vmcnt(0)
	s_barrier
	s_and_saveexec_b64 s[0:1], s[52:53]
	v_readlane_b32 s14, v255, 14
	v_readlane_b32 s16, v255, 16
	v_readlane_b32 s15, v255, 15
	v_readlane_b32 s17, v255, 17
	s_add_i32 s101, s101, 1
	s_cbranch_execz .LBB0_918
	v_readlane_b32 s98, v253, 2
	v_readlane_b32 s99, v253, 3
	s_nop 0
	s_add_u32 s98, s98, 0x7c000
	s_addc_u32 s99, s99, 0
	s_and_b32 vcc_lo, s2, 63
	s_lshl_b32 vcc_lo, vcc_lo, 8
	s_add_u32 vcc_lo, vcc_lo, 0x2000
	v_mov_b32_e32 v3, vcc_lo
	v_mov_b32_e32 v4, 1
	s_lshl_b32 vcc_hi, s101, 2
	s_waitcnt vmcnt(0) lgkmcnt(0)
	global_atomic_add v5, v3, v4, s[98:99] sc0
	s_waitcnt vmcnt(0)
	v_readfirstlane_b32 vcc_lo, v5
	s_add_i32 vcc_lo, vcc_lo, 1
	s_cmp_ge_u32 vcc_lo, vcc_hi
	s_cbranch_scc1 .Lb3_ok_7

.Lb3_p_7:
	global_load_dword v5, v3, s[98:99] sc1
	s_waitcnt vmcnt(0)
	v_readfirstlane_b32 vcc_lo, v5
	s_cmp_ge_u32 vcc_lo, vcc_hi
	s_cbranch_scc1 .Lb3_ok_7
	s_sleep 1
	s_sub_u32 m0, m0, 1
	s_cmp_eq_u32 m0, 0
	s_cbranch_scc0 .Lb3_p_7

.LBB0_954:
	s_getreg_b32 s0, hwreg(HW_REG_XCC_ID, 0, 4)
	s_and_b32 s10, s0, 15
	s_waitcnt vmcnt(0)
	s_barrier
	s_and_saveexec_b64 s[0:1], s[52:53]
	v_readlane_b32 s28, v255, 14
	v_readlane_b32 s14, v255, 16
	v_readlane_b32 s29, v255, 15
	v_readlane_b32 s15, v255, 17
	s_add_i32 s101, s101, 1
	s_cbranch_execz .LBB0_1006
	v_readlane_b32 s98, v253, 2
	v_readlane_b32 s99, v253, 3
	s_nop 0
	s_add_u32 s98, s98, 0x7c000
	s_addc_u32 s99, s99, 0
	s_and_b32 vcc_lo, s2, 63
	s_lshl_b32 vcc_lo, vcc_lo, 8
	s_add_u32 vcc_lo, vcc_lo, 0x2000
	v_mov_b32_e32 v3, vcc_lo
	v_mov_b32_e32 v4, 1
	s_lshl_b32 vcc_hi, s101, 2
	s_waitcnt vmcnt(0) lgkmcnt(0)
	global_atomic_add v5, v3, v4, s[98:99] sc0
	s_waitcnt vmcnt(0)
	v_readfirstlane_b32 vcc_lo, v5
	s_add_i32 vcc_lo, vcc_lo, 1
	s_cmp_ge_u32 vcc_lo, vcc_hi
	s_cbranch_scc1 .Lb3_ok_8

.LBB0_1067:
	s_getreg_b32 s0, hwreg(HW_REG_XCC_ID, 0, 4)
	s_and_b32 s10, s0, 15
	s_waitcnt vmcnt(0)
	s_barrier
	s_and_saveexec_b64 s[0:1], s[52:53]
	v_readlane_b32 s22, v255, 16
	v_readlane_b32 s23, v255, 17
	s_add_i32 s100, s100, 1
	s_cbranch_execz .LBB0_1119
	v_readlane_b32 s98, v253, 2
	v_readlane_b32 s99, v253, 3
	s_nop 0
	s_add_u32 s98, s98, 0x7c000
	s_addc_u32 s99, s99, 0
	s_and_b32 vcc_hi, s2, 7
	s_sub_u32 vcc_lo, 7, vcc_hi
	s_add_u32 vcc_lo, vcc_lo, s3
	s_lshr_b32 vcc_lo, vcc_lo, 3
	s_mul_i32 vcc_lo, vcc_lo, s100
	s_lshl_b32 vcc_hi, vcc_hi, 8
	v_mov_b32_e32 v2, vcc_hi
	v_mov_b32_e32 v4, 1
	s_waitcnt vmcnt(0) lgkmcnt(0)
	global_atomic_add v5, v2, v4, s[98:99] sc0
	v_add_u32_e32 v3, 0x900, v2
	s_waitcnt vmcnt(0)
	v_readfirstlane_b32 vcc_hi, v5
	s_add_i32 vcc_hi, vcc_hi, 1
	s_cmp_eq_u32 vcc_hi, vcc_lo
	s_cbranch_scc0 .Lb3_poll_9
	v_mov_b32_e32 v6, 0x800
	global_atomic_add v5, v6, v4, s[98:99] sc0
	s_min_u32 vcc_lo, s3, 8
	s_mul_i32 vcc_lo, vcc_lo, s100
	s_waitcnt vmcnt(0)
	v_readfirstlane_b32 vcc_hi, v5
	s_add_i32 vcc_hi, vcc_hi, 1
	s_cmp_eq_u32 vcc_hi, vcc_lo
	s_cbranch_scc0 .Lb3_poll_9
	v_mov_b32_e32 v6, 0x900
	global_atomic_add v6, v4, s[98:99]
	global_atomic_add v6, v4, s[98:99] offset:256
	global_atomic_add v6, v4, s[98:99] offset:512
	global_atomic_add v6, v4, s[98:99] offset:768
	global_atomic_add v6, v4, s[98:99] offset:1024
	global_atomic_add v6, v4, s[98:99] offset:1280
	global_atomic_add v6, v4, s[98:99] offset:1536
	global_atomic_add v6, v4, s[98:99] offset:1792

.LBB0_1156:
	s_getreg_b32 s0, hwreg(HW_REG_XCC_ID, 0, 4)
	s_and_b32 s4, s0, 15
	s_waitcnt vmcnt(0)
	s_waitcnt vmcnt(0)
	s_barrier
	s_and_saveexec_b64 s[0:1], s[52:53]
	s_add_i32 s100, s100, 1
	s_cbranch_execz .LBB0_1208
	v_readlane_b32 s98, v253, 2
	v_readlane_b32 s99, v253, 3
	s_nop 0
	s_add_u32 s98, s98, 0x7c000
	s_addc_u32 s99, s99, 0
	s_and_b32 vcc_hi, s2, 7
	s_sub_u32 vcc_lo, 7, vcc_hi
	s_add_u32 vcc_lo, vcc_lo, s3
	s_lshr_b32 vcc_lo, vcc_lo, 3
	s_mul_i32 vcc_lo, vcc_lo, s100
	s_lshl_b32 vcc_hi, vcc_hi, 8
	v_mov_b32_e32 v2, vcc_hi
	v_mov_b32_e32 v4, 1
	s_waitcnt vmcnt(0) lgkmcnt(0)
	global_atomic_add v5, v2, v4, s[98:99] sc0
	v_add_u32_e32 v3, 0x900, v2
	s_waitcnt vmcnt(0)
	v_readfirstlane_b32 vcc_hi, v5
	s_add_i32 vcc_hi, vcc_hi, 1
	s_cmp_eq_u32 vcc_hi, vcc_lo
	s_cbranch_scc0 .Lb3_poll_10
	v_mov_b32_e32 v6, 0x800
	global_atomic_add v5, v6, v4, s[98:99] sc0
	s_min_u32 vcc_lo, s3, 8
	s_mul_i32 vcc_lo, vcc_lo, s100
	s_waitcnt vmcnt(0)
	v_readfirstlane_b32 vcc_hi, v5
	s_add_i32 vcc_hi, vcc_hi, 1
	s_cmp_eq_u32 vcc_hi, vcc_lo
	s_cbranch_scc0 .Lb3_poll_10
	v_mov_b32_e32 v6, 0x900
	global_atomic_add v6, v4, s[98:99]
	global_atomic_add v6, v4, s[98:99] offset:256
	global_atomic_add v6, v4, s[98:99] offset:512
	global_atomic_add v6, v4, s[98:99] offset:768
	global_atomic_add v6, v4, s[98:99] offset:1024
	global_atomic_add v6, v4, s[98:99] offset:1280
	global_atomic_add v6, v4, s[98:99] offset:1536
	global_atomic_add v6, v4, s[98:99] offset:1792

.LBB0_1337:
	v_readlane_b32 s34, v255, 14
	v_readlane_b32 s22, v255, 16
	s_and_b64 vcc, exec, s[38:39]
	s_mov_b64 s[0:1], -1
	v_readlane_b32 s35, v255, 15
	v_readlane_b32 s23, v255, 17
	s_cbranch_vccnz .LBB0_1391
	s_getreg_b32 s0, hwreg(HW_REG_XCC_ID, 0, 4)
	s_and_b32 s10, s0, 15
	s_waitcnt vmcnt(0)
	s_barrier
	s_and_saveexec_b64 s[0:1], s[52:53]
	s_add_i32 s100, s100, 1
	s_cbranch_execz .LBB0_1390
	v_readlane_b32 s98, v253, 2
	v_readlane_b32 s99, v253, 3
	s_nop 0
	s_add_u32 s98, s98, 0x7c000
	s_addc_u32 s99, s99, 0
	s_and_b32 vcc_hi, s2, 7
	s_sub_u32 vcc_lo, 7, vcc_hi
	s_add_u32 vcc_lo, vcc_lo, s3
	s_lshr_b32 vcc_lo, vcc_lo, 3
	s_mul_i32 vcc_lo, vcc_lo, s100
	s_lshl_b32 vcc_hi, vcc_hi, 8
	v_mov_b32_e32 v2, vcc_hi
	v_mov_b32_e32 v4, 1
	s_waitcnt vmcnt(0) lgkmcnt(0)
	global_atomic_add v5, v2, v4, s[98:99] sc0
	v_add_u32_e32 v3, 0x900, v2
	s_waitcnt vmcnt(0)
	v_readfirstlane_b32 vcc_hi, v5
	s_add_i32 vcc_hi, vcc_hi, 1
	s_cmp_eq_u32 vcc_hi, vcc_lo
	s_cbranch_scc0 .Lb3_poll_11
	v_mov_b32_e32 v6, 0x800
	global_atomic_add v5, v6, v4, s[98:99] sc0
	s_min_u32 vcc_lo, s3, 8
	s_mul_i32 vcc_lo, vcc_lo, s100
	s_waitcnt vmcnt(0)
	v_readfirstlane_b32 vcc_hi, v5
	s_add_i32 vcc_hi, vcc_hi, 1
	s_cmp_eq_u32 vcc_hi, vcc_lo
	s_cbranch_scc0 .Lb3_poll_11
	v_mov_b32_e32 v6, 0x900
	global_atomic_add v6, v4, s[98:99]
	global_atomic_add v6, v4, s[98:99] offset:256
	global_atomic_add v6, v4, s[98:99] offset:512
	global_atomic_add v6, v4, s[98:99] offset:768
	global_atomic_add v6, v4, s[98:99] offset:1024
	global_atomic_add v6, v4, s[98:99] offset:1280
	global_atomic_add v6, v4, s[98:99] offset:1536
	global_atomic_add v6, v4, s[98:99] offset:1792
